# PE->PS grid barrier removed: PS items remapped to the chunk the block's own PE wrote (b=bid>>6, all heads), workgroup barrier instead
# speedup vs baseline: 1.0111x; 1.0059x over previous
; #define LAS __attribute__((address_space(3)))
; DI unsigned xb_ld(unsigned* p)              { return __hip_atomic_load(p, __ATOMIC_RELAXED, __HIP_MEMORY_SCOPE_AGENT); }
; DI unsigned xb_add(unsigned* p, unsigned v) { return __hip_atomic_fetch_add(p, v, __ATOMIC_RELAXED, __HIP_MEMORY_SCOPE_AGENT); }
; DI unsigned xb_xcc_id() { return (unsigned)__builtin_amdgcn_s_getreg((3 << 11) | 20) & 0xFu; }
; #define RUN(...) RUNR(1, __VA_ARGS__)
; __global__ void __launch_bounds__(NT, 2) fwd_megakernel(Params p) {
;     ...
;     const int G = gridDim.x, bid = blockIdx.x;
;     const int lo = p.ph_lo;
;     const bool fuse_pf = (G == 256) && (p.ph_lo == 0) && (p.ph_hi == N_PHASES);
;     const int hi = fuse_pf ? p.ph_hi - 1 : p.ph_hi;
;     int ph = 0, nsync = 0;
;     volatile LAS unsigned* xst = (volatile LAS unsigned*)(lds + LDS_BYTES - 16);
;     if (threadIdx.x < 4) xst[threadIdx.x] = 0u;
;     __syncthreads();
;     XcdBarrier xbar = xcd_barrier_post((unsigned*)(p.ws + WS_BAR), xst);
;     unsigned* slotw = (unsigned*)(p.ws + WS_BAR) + XCD_BAR_WORDS;
;     if (threadIdx.x == 0) { const unsigned xc = xb_xcc_id() & 7u; xst[2] = xc; xst[3] = xb_add(&slotw[64 * xc], 1u); }
;     ...
;     RUNR(REP_P0, phase0(p, lds, G, bid));
;     int vb = bid, vc = bid;
;     if (G == 256 && lo == 0 && hi > 1) {
;         bool ok = true;
;         for (int j = 0; j < 8; ++j) ok = ok && (xb_ld(&slotw[64 * j]) == 32u);
;         if (ok) { const int xc = (int)xst[2], sl = (int)xst[3]; vb = xc * 32 + sl; vc = sl * 8 + xc; }
;     }
;     vb = __builtin_amdgcn_readfirstlane(vb); vc = __builtin_amdgcn_readfirstlane(vc);
;     for (int l = 0; l < 2; ++l) {
;         const float* xin = (l == 0) ? p.x : p.out;
;         RUNR(REP_PN, phase_norm(p, l, xin, lds, G, bid));
;         for (int seg = 0; seg < NSEG; ++seg) {
;             RUNR(REP_G1, { phase_tables(p, l, seg, G, bid); pg8::Gemm g{(const bf16_t*)(p.ws + WS_H), (const bf16_t*)(p.ws + WS_WIN) + (size_t)l * NPC * D, D, D, MSEG / 256, NPC / 256, seg, 0};
;                   pg8::EpiP E{(bf16_t*)(p.ws + WS_P), p.pos, (const float*)(p.ws + WS_INVF), seg};
;                   pg8::gemm_phase(lds, g, G, vc, E); });
;             RUNR(REP_PE, phase_prep(p, l, seg, lds, G, bid));
;             RUN(phase_ps(p, seg, lds, G, bid));
;             RUNR(REP_MX, phase_mixer(p, seg, lds, G, vb));
.LBB0_118:
	s_lshl_b32 s8, s53, 3
	s_lshl_b32 s10, s94, 3
	s_add_u32 s0, s92, 0x100000
	v_writelane_b32 v252, s0, 12
	s_addc_u32 s0, s93, 0
	v_writelane_b32 v252, s0, 13
	s_add_u32 s0, s92, 0x180000
	v_writelane_b32 v252, s0, 14
	s_addc_u32 s0, s93, 0
	v_writelane_b32 v252, s0, 15
	s_add_u32 s0, s92, 0x4000000
	v_writelane_b32 v252, s0, 16
	s_addc_u32 s0, s93, 0
	v_writelane_b32 v252, s0, 17
	s_add_u32 s0, s92, 0x200000
	s_addc_u32 s1, s93, 0
	v_writelane_b32 v252, s0, 18
	v_readfirstlane_b32 s9, v2
	s_waitcnt lgkmcnt(0)
	s_movk_i32 s79, 0x3ff
	v_writelane_b32 v252, s1, 19
	s_mov_b32 s27, 0
	v_readlane_b32 s0, v252, 4
	v_readlane_b32 s1, v252, 5
	s_cmp_gt_i32 s0, -1
	s_cselect_b64 s[0:1], -1, 0
	v_writelane_b32 v252, s0, 20
	v_mbcnt_lo_u32_b32 v2, -1, 0
	s_mov_b32 s95, s9
	v_writelane_b32 v252, s1, 21
	s_add_u32 s0, s92, 0x200
	s_addc_u32 s1, s93, 0
	v_writelane_b32 v252, s0, 22
	v_mov_b32_e32 v204, 0x358637bd
	v_mov_b32_e32 v205, 0x260
	v_writelane_b32 v252, s1, 23
	s_add_u32 s0, s92, 0x1000
	s_addc_u32 s1, s93, 0
	v_writelane_b32 v252, s0, 24
	v_mov_b32_e32 v206, 1
	v_mov_b32_e32 v207, 0x3ecc95a3
	v_writelane_b32 v252, s1, 25
	s_add_u32 s0, s92, 0x1100
	s_addc_u32 s1, s93, 0
	v_writelane_b32 v252, s0, 26
	v_mov_b32_e32 v208, 0x480000
	v_mbcnt_hi_u32_b32 v203, -1, v2
	v_writelane_b32 v252, s1, 27
	s_add_u32 s0, s92, 0x1200
	s_addc_u32 s1, s93, 0
	v_writelane_b32 v252, s0, 28
	v_mov_b32_e32 v209, 0x7f800000
	v_mov_b32_e32 v162, 0x3f317218
	v_writelane_b32 v252, s1, 29
	s_add_u32 s0, s92, 0x1300
	s_addc_u32 s1, s93, 0
	v_writelane_b32 v252, s0, 30
	s_cmp_eq_u32 s26, 15
	v_mov_b64_e32 v[164:165], 0x900
	v_writelane_b32 v252, s1, 31
	s_cselect_b64 s[0:1], -1, 0
	v_writelane_b32 v252, s0, 32
	s_cmp_eq_u32 s26, 14
	v_mov_b64_e32 v[166:167], 0x8ff
	v_writelane_b32 v252, s1, 33
	s_cselect_b64 s[0:1], -1, 0
	v_writelane_b32 v252, s0, 34
	s_cmp_eq_u32 s26, 13
	v_mov_b32_e32 v210, 0x42800000
	v_writelane_b32 v252, s1, 35
	s_cselect_b64 s[0:1], -1, 0
	v_writelane_b32 v252, s0, 36
	s_cmp_eq_u32 s26, 12
	v_mov_b32_e32 v211, 0x42000000
	v_writelane_b32 v252, s1, 37
	s_cselect_b64 s[0:1], -1, 0
	v_writelane_b32 v252, s0, 38
	s_cmp_eq_u32 s26, 11
	v_not_b32_e32 v212, 63
	v_writelane_b32 v252, s1, 39
	s_cselect_b64 s[0:1], -1, 0
	v_writelane_b32 v252, s0, 40
	s_cmp_eq_u32 s26, 10
	v_mov_b32_e32 v213, 0x3d800000
	v_writelane_b32 v252, s1, 41
	s_cselect_b64 s[0:1], -1, 0
	v_writelane_b32 v252, s0, 42
	s_cmp_eq_u32 s26, 9
	v_mov_b32_e32 v214, 0x3f80
	v_writelane_b32 v252, s1, 43
	s_cselect_b64 s[0:1], -1, 0
	v_writelane_b32 v252, s0, 44
	s_cmp_eq_u32 s26, 8
	v_mov_b32_e32 v215, 0xc000
	v_writelane_b32 v252, s1, 45
	s_cselect_b64 s[0:1], -1, 0
	v_writelane_b32 v252, s0, 46
	s_cmp_eq_u32 s26, 7
	v_mov_b32_e32 v216, 0x2000
	v_writelane_b32 v252, s1, 47
	s_cselect_b64 s[0:1], -1, 0
	v_writelane_b32 v252, s0, 48
	s_cmp_eq_u32 s26, 6
	v_mov_b32_e32 v217, 0xc00
	v_writelane_b32 v252, s1, 49
	s_cselect_b64 s[0:1], -1, 0
	v_writelane_b32 v252, s0, 50
	s_cmp_eq_u32 s26, 5
	v_mov_b64_e32 v[168:169], 0x100
	v_writelane_b32 v252, s1, 51
	s_cselect_b64 s[0:1], -1, 0
	v_writelane_b32 v252, s0, 52
	s_cmp_eq_u32 s26, 4
	v_mov_b64_e32 v[170:171], 0xff
	v_writelane_b32 v252, s1, 53
	s_cselect_b64 s[0:1], -1, 0
	v_writelane_b32 v252, s0, 54
	s_cmp_eq_u32 s26, 3
	s_movk_i32 s82, 0x90
	v_writelane_b32 v252, s1, 55
	s_cselect_b64 s[0:1], -1, 0
	v_writelane_b32 v252, s0, 56
	s_cmp_eq_u32 s26, 2
	s_movk_i32 s96, 0x4800
	v_writelane_b32 v252, s1, 57
	s_cselect_b64 s[0:1], -1, 0
	v_writelane_b32 v252, s0, 58
	s_cmp_eq_u32 s26, 1
	s_movk_i32 s85, 0xdff
	v_writelane_b32 v252, s1, 59
	s_cselect_b64 s[0:1], -1, 0
	v_writelane_b32 v252, s0, 60
	s_cmp_eq_u32 s26, 0
	s_movk_i32 s89, 0x2000
	v_writelane_b32 v252, s1, 61
	s_cselect_b64 s[0:1], -1, 0
	v_writelane_b32 v252, s0, 62
	s_mov_b32 s39, 0x3fb8aa3b
	s_mov_b32 s16, 0xc2fc0000
	v_writelane_b32 v252, s1, 63
	s_lshl_b32 s0, s26, 8
	s_add_u32 s0, s92, s0
	s_addc_u32 s1, s93, 0
	s_add_u32 s2, s0, 0x1400
	s_addc_u32 s3, s1, 0
	v_writelane_b32 v251, s2, 0
	v_readlane_b32 s12, v252, 6
	v_readlane_b32 s13, v252, 7
	v_writelane_b32 v251, s3, 1
	s_add_u32 s2, s92, 0x3500
	s_addc_u32 s3, s93, 0
	v_writelane_b32 v251, s2, 2
	s_mov_b32 s26, s27
	s_mov_b32 s58, 0x42fc0000
	v_writelane_b32 v251, s3, 3
	s_add_u32 s2, s92, 0x3400
	s_addc_u32 s3, s93, 0
	s_add_u32 s0, s0, 0x2400
	v_writelane_b32 v251, s2, 4
	s_addc_u32 s1, s1, 0
	s_add_u32 s20, s92, 0x300000
	v_writelane_b32 v251, s3, 5
	v_writelane_b32 v251, s0, 6
	s_addc_u32 s21, s93, 0
	s_movk_i32 s34, 0x210
	v_writelane_b32 v251, s1, 7
	s_add_u32 s0, s92, 0x4c0000
	s_addc_u32 s1, s93, 0
	v_writelane_b32 v251, s0, 8
	s_movk_i32 s59, 0x2400
	s_movk_i32 s37, 0xa0
	v_writelane_b32 v251, s1, 9
	s_add_u32 s0, s92, 0x1000000
	v_writelane_b32 v251, s0, 10
	s_addc_u32 s0, s93, 0
	s_add_u32 s24, s92, 0xc000000
	s_addc_u32 s25, s93, 0
	v_writelane_b32 v251, s0, 11
	s_add_u32 s0, s92, 0x120000
	v_writelane_b32 v251, s0, 12
	s_addc_u32 s0, s93, 0
	v_writelane_b32 v251, s0, 13
	s_ashr_i32 s0, s9, 31
	s_cmpk_lt_i32 s9, 0x900
	s_cselect_b64 s[2:3], -1, 0
	s_mov_b32 s7, s0
	s_lshr_b32 s0, s0, 29
	s_add_i32 s0, s9, s0
	s_ashr_i32 s1, s0, 3
	s_and_b32 s0, s0, -8
	v_writelane_b32 v251, s2, 14
	s_sub_i32 s0, s9, s0
	s_mov_b64 s[56:57], 0x120000
	v_writelane_b32 v251, s3, 15
	s_lshl_b32 s2, s0, 5
	s_cmp_lt_i32 s0, 0
	s_movk_i32 s3, 0x121
	s_cselect_b32 s3, s3, 0x120
	s_mul_i32 s3, s3, s0
	s_mul_i32 s0, s0, 33
	s_cselect_b32 s4, s0, s2
	s_add_i32 s3, s3, s1
	s_mul_hi_i32 s0, s3, 0x38e38e39
	s_lshr_b32 s2, s0, 31
	s_ashr_i32 s0, s0, 5
	s_add_i32 s0, s0, s2
	s_mul_i32 s2, s0, 0x90
	s_sub_i32 s2, s3, s2
	s_bfe_u32 s3, s2, 0x2001d
; DI void tables_stage2(const Params& p, int seg, LAS float* mtab, int bid) {
;     ...
;     const bool narrow = (gridDim.x == 256);
;     const int t_lo = narrow ? 4 * (bid >> 6) + wave : wave, t_hi = narrow ? (wave < 4 ? t_lo + 1 : 0) : NB * 4;
;     const bool pub = narrow ? ((bid & 63) == 0) : (bid == 0);
; DI void phase_ps(const Params& p, int seg, LAS unsigned char* lds, int G, int bid) {
;     ...
;     int item = bid;
;     if (item < NITEM) PS_LOAD(item);
	s_add_i32 s3, s2, s3
	s_and_b32 s5, s3, 0xfffc
	s_sub_i32 s2, s2, s5
	s_lshl_b32 s0, s0, 2
	s_sext_i32_i16 s2, s2
	s_add_i32 s6, s0, s2
	s_sext_i32_i16 s0, s3
	s_ashr_i32 s2, s0, 2
	s_lshr_b32 s0, s0, 2
	s_ashr_i32 s35, s94, 31
	v_writelane_b32 v251, s2, 16
	s_add_u32 s2, s92, 0x480000
	s_addc_u32 s3, s93, 0
	v_writelane_b32 v251, s2, 17
	s_mov_b64 s[14:15], 0x80
	s_mov_b64 s[54:55], 0x400
	v_writelane_b32 v251, s3, 18
	s_add_u32 s2, s92, 0x141000
	s_addc_u32 s3, s93, 0
	v_writelane_b32 v251, s2, 19
	s_nop 1
	v_writelane_b32 v251, s3, 20
	s_ashr_i32 s2, s53, 4
	s_and_b32 s5, s2, -4
	s_and_b64 s[2:3], s[12:13], exec
	s_cselect_b32 s2, s5, 0
	s_and_b32 s5, s53, 63
	v_writelane_b32 v251, s2, 21
	s_and_b64 s[2:3], s[12:13], exec
	s_cselect_b32 s2, s5, s53
	s_cmp_eq_u32 s2, 0
	s_cselect_b64 s[2:3], -1, 0
	v_writelane_b32 v251, s2, 22
	s_nop 1
	v_writelane_b32 v251, s3, 23
	s_add_u32 s2, s92, 0x8000000
	s_addc_u32 s3, s93, 0
	v_writelane_b32 v251, s2, 24
	s_nop 1
	v_writelane_b32 v251, s3, 25
	s_add_u32 s2, s92, 0x121000
	s_addc_u32 s3, s93, 0
	v_writelane_b32 v251, s2, 26
	s_lshl_b32 s78, s94, 9
	s_nop 0
	v_writelane_b32 v251, s3, 27
	s_lshl_b32 s2, s53, 9
	v_writelane_b32 v251, s2, 28
	s_add_u32 s2, s92, 0x580000
	s_addc_u32 s3, s93, 0
	v_writelane_b32 v251, s2, 29
	s_cmpk_lt_i32 s53, 0x800
	s_nop 0
	v_writelane_b32 v251, s3, 30
	s_cselect_b64 s[2:3], -1, 0
	v_writelane_b32 v251, s2, 31
	s_nop 1
	v_writelane_b32 v251, s3, 32
	s_ashr_i32 s2, s53, 31
	s_lshr_b32 s2, s2, 26
	s_add_i32 s2, s53, s2
	s_ashr_i32 s3, s2, 6
	s_and_b32 s2, s2, 0x3ffffc0
	s_sub_i32 s2, s53, s2
	s_cmp_gt_u32 s3, 15
	s_cselect_b64 s[12:13], -1, 0
	s_lshl_b32 s5, s3, 7
	v_writelane_b32 v251, s12, 33
	s_and_b32 s5, s5, 0x600
	s_add_u32 s5, s92, s5
	v_writelane_b32 v251, s13, 34
	v_writelane_b32 v251, s5, 35
	s_addc_u32 s5, s93, 0
	s_lshl_b32 s3, s3, 12
	s_and_b32 s3, s3, 0x3000
	s_lshl_b32 s2, s2, 6
	v_writelane_b32 v251, s5, 36
	s_add_i32 s2, s3, s2
	v_writelane_b32 v251, s2, 37
	s_add_u32 s2, s92, 0x500000
	s_addc_u32 s3, s93, 0
	v_readfirstlane_b32 s5, v1
	v_writelane_b32 v251, s2, 38
	s_cmpk_lt_i32 s5, 0x100
	v_lshrrev_b32_e32 v1, 20, v0
	v_writelane_b32 v251, s3, 39
	s_cselect_b64 s[2:3], -1, 0
	v_writelane_b32 v251, s2, 40
	v_lshrrev_b32_e32 v0, 10, v0
	v_or_b32_e32 v0, v0, v1
	v_writelane_b32 v251, s3, 41
	s_add_u32 s2, s92, 0x1e000000
	s_addc_u32 s3, s93, 0
	v_writelane_b32 v251, s2, 42
	v_and_or_b32 v0, v0, s79, v202
	v_mov_b32_e32 v1, 0
	v_writelane_b32 v251, s3, 43
	s_add_u32 s2, s92, 0x3400000
	v_writelane_b32 v251, s2, 44
	s_addc_u32 s2, s93, 0
	s_cmpk_lt_i32 s9, 0x100
	v_writelane_b32 v251, s2, 45
	s_cselect_b64 s[2:3], -1, 0
	v_writelane_b32 v251, s2, 46
	s_mov_b64 s[12:13], 0
	s_nop 0
	v_writelane_b32 v251, s3, 47
	s_add_u32 s2, s92, 0x10e000
	v_writelane_b32 v251, s2, 48
	s_addc_u32 s2, s93, 0
	v_writelane_b32 v251, s2, 49
	s_add_u32 s2, s92, 0x600000
	v_writelane_b32 v251, s2, 50
	s_addc_u32 s2, s93, 0
	v_writelane_b32 v251, s2, 51
	s_add_u32 s2, s92, 0x4000
	v_writelane_b32 v251, s2, 52
	s_addc_u32 s2, s93, 0
	v_writelane_b32 v251, s2, 53
	s_bfe_i32 s2, s6, 0x10017
	s_lshr_b32 s2, s2, 20
	s_lshl_b32 s3, s6, 8
	s_add_i32 s2, s3, s2
	s_and_b32 s2, s2, 0xfffff000
	s_sub_i32 s2, s3, s2
	s_ashr_i32 s3, s6, 31
	s_lshr_b32 s3, s3, 28
	s_add_i32 s3, s6, s3
	s_lshl_b32 s3, s3, 9
	s_and_b32 s3, s3, 0xffffe000
	v_writelane_b32 v251, s6, 54
	s_add_i32 s2, s2, s3
	s_add_i32 s1, s4, s1
	v_writelane_b32 v251, s2, 55
	s_ashr_i32 s2, s1, 31
	s_lshr_b32 s2, s2, 28
	s_add_i32 s2, s1, s2
	s_and_b32 s3, s2, 0xfff0
	s_sub_i32 s1, s1, s3
	s_bfe_i32 s3, s1, 0x80000
	s_bfe_u32 s3, s3, 0x2000d
	s_add_i32 s3, s1, s3
	s_and_b32 s4, s3, 0xfc
	s_sub_i32 s1, s1, s4
	s_ashr_i32 s2, s2, 4
	s_lshl_b32 s2, s2, 2
	s_sext_i32_i8 s1, s1
	s_add_i32 s4, s2, s1
	s_bfe_i64 s[0:1], s[0:1], 0x100000
	s_lshl_b64 s[0:1], s[0:1], 19
	v_writelane_b32 v251, s0, 56
	s_mov_b32 s6, 1
	s_nop 0
	v_writelane_b32 v251, s1, 57
	s_bfe_i32 s0, s3, 0x80000
	s_sext_i32_i16 s0, s0
	s_lshl_b32 s1, s4, 8
	s_mul_hi_i32 s2, s1, 0x4800
	s_ashr_i32 s1, s0, 2
	s_lshr_b32 s0, s0, 2
	v_writelane_b32 v251, s1, 58
	s_bfe_i64 s[0:1], s[0:1], 0x100000
	s_lshl_b64 s[0:1], s[0:1], 20
	v_writelane_b32 v251, s0, 59
	s_nop 1
	v_writelane_b32 v251, s1, 60
	s_mul_i32 s0, s4, 0x480000
	s_add_u32 s0, s24, s0
	s_addc_u32 s1, s25, s2
	v_writelane_b32 v251, s4, 61
	s_add_u32 s2, s0, 0x240000
	v_writelane_b32 v251, s0, 62
	s_addc_u32 s3, s1, 0
	v_writelane_b32 v250, s2, 0
	v_writelane_b32 v251, s1, 63
	s_mov_b32 s0, s8
	v_writelane_b32 v250, s3, 1
	v_writelane_b32 v250, s0, 2
	s_ashr_i32 s11, s10, 31
	s_lshl_b32 s83, s94, 12
	v_writelane_b32 v250, s1, 3
	s_add_i32 s0, s8, s10
	v_writelane_b32 v250, s0, 4
	s_lshl_b32 s0, s53, 12
	v_writelane_b32 v250, s0, 5
	s_lshl_b32 s0, s53, 6
	v_writelane_b32 v250, s0, 6
	v_writelane_b32 v250, s5, 7
	s_lshl_b32 s0, s5, 3
	v_writelane_b32 v250, s0, 8
	s_add_i32 s0, 0, 0x23ff0
	v_writelane_b32 v250, s0, 9
	s_add_i32 s0, 0, 0x23ff4
	v_writelane_b32 v250, s0, 10
	s_add_i32 s0, 0, 0x16b00
	v_writelane_b32 v250, s0, 11
	s_add_i32 s0, 0, 0x18700
	v_writelane_b32 v250, s0, 12
	v_cmp_eq_u32_e64 s[0:1], 0, v0
	s_add_i32 s36, 0, 0x18c00
	s_mov_b64 s[2:3], -1
	v_writelane_b32 v250, s0, 13
	s_nop 1
	v_writelane_b32 v250, s1, 14
	s_lshl_b64 s[0:1], s[10:11], 5
	v_writelane_b32 v250, s0, 15
	s_nop 1
	v_writelane_b32 v250, s1, 16
	s_lshl_b64 s[0:1], s[10:11], 11
	v_writelane_b32 v250, s0, 17
	s_nop 1
	v_writelane_b32 v250, s1, 18
	s_lshl_b64 s[0:1], s[10:11], 12
	v_writelane_b32 v250, s0, 19
	s_nop 1
	v_writelane_b32 v250, s1, 20
	v_writelane_b32 v250, s97, 21
	v_writelane_b32 v250, s35, 22
	v_writelane_b32 v250, s78, 23
	v_writelane_b32 v250, s83, 24
	s_branch .LBB0_120

; #define RUNR(rep, ...) do { if (ph >= lo && ph < hi) { for (int r_ = 0; r_ < (rep); ++r_) { __VA_ARGS__; if (r_ + 1 < (rep) || ph + 1 < hi) GSYNC(); } } ++ph; } while (0)
; #define RUN(...) RUNR(1, __VA_ARGS__)
; __global__ void __launch_bounds__(NT, 2) fwd_megakernel(Params p) {
;     ...
;             RUNR(REP_PE, phase_prep(p, l, seg, lds, G, bid));
;             RUN(phase_ps(p, seg, lds, G, bid));
.LBB0_421:
	s_or_b64 exec, exec, s[0:1]
	v_readlane_b32 s0, v250, 58
	s_add_i32 s8, s0, 3
	s_cmp_ge_i32 s8, s33
	s_cbranch_scc1 .LBB0_489
	v_readlane_b32 s18, v252, 20
	v_readlane_b32 s19, v252, 21
	s_mov_b64 s[0:1], -1
	s_and_b64 vcc, exec, s[18:19]
	s_cbranch_vccz .LBB0_476
	s_waitcnt vmcnt(0)
	s_mov_b64 s[0:1], 0
	s_barrier

; #define LAS __attribute__((address_space(3)))
; DI void phase_ps(const Params& p, int seg, LAS unsigned char* lds, int G, int bid) {
;     ...
;         { int ts_ = tid; asm volatile("" : "+v"(ts_));
; #pragma unroll
;           for (int i = 0; i < 4; ++i) { const int idx = ts_ + 512 * i, row = idx >> 5, c16 = idx & 31;
;               *(LAS u32x4*)(lds + PS_QI + row * QP + c16 * 16) = pq[i]; *(LAS u32x4*)(lds + PS_KI + row * QP + c16 * 16) = pk[i]; *(LAS u32x4*)(lds + PS_VI + row * QP + c16 * 16) = pv[i]; } }
;         if (item + G < NITEM) PS_LOAD(item + G);
.LBB0_496:
	v_mov_b32_e32 v0, v90
	s_add_i32 s6, 0, 0x10800
	v_lshlrev_b32_e32 v50, 4, v0
	v_and_b32_e32 v50, 0x1f0, v50
	v_ashrrev_i32_e32 v52, 5, v0
	v_add_u32_e32 v51, 0, v50
	v_add_u32_e32 v50, s6, v50
	v_mul_lo_u32 v52, v52, s34
	v_add_u32_e32 v53, v51, v52
	v_add_u32_e32 v52, v50, v52
	s_waitcnt vmcnt(0)
	ds_write_b128 v53, v[14:17]
	ds_write_b128 v53, v[10:13] offset:33792
	ds_write_b128 v52, v[34:37]
	v_add_u32_e32 v52, 0x200, v0
	v_ashrrev_i32_e32 v52, 5, v52
	v_mul_lo_u32 v52, v52, s34
	v_add_u32_e32 v53, v51, v52
	v_add_u32_e32 v52, v50, v52
	ds_write_b128 v53, v[38:41]
	ds_write_b128 v53, v[22:25] offset:33792
	ds_write_b128 v52, v[18:21]
	v_add_u32_e32 v52, 0x400, v0
	v_add_u32_e32 v0, 0x600, v0
	s_add_i32 s39, s22, s94
	v_ashrrev_i32_e32 v52, 5, v52
	v_ashrrev_i32_e32 v0, 5, v0
	s_cmpk_gt_i32 s39, 0x7ff
	v_mul_lo_u32 v52, v52, s34
	v_mul_lo_u32 v0, v0, s34
	s_cselect_b64 s[44:45], -1, 0
	v_add_u32_e32 v53, v51, v52
	v_add_u32_e32 v52, v50, v52
	v_add_u32_e32 v51, v51, v0
	v_add_u32_e32 v0, v50, v0
	s_and_b64 vcc, exec, s[44:45]
	ds_write_b128 v53, v[30:33]
	ds_write_b128 v53, v[26:29] offset:33792
	ds_write_b128 v52, v[42:45]
	ds_write_b128 v51, v[46:49]
	ds_write_b128 v51, v[6:9] offset:33792
	ds_write_b128 v0, v[2:5]
	s_cbranch_vccnz .LBB0_498
	s_ashr_i32 s6, s39, 31
	s_lshr_b32 s6, s6, 26
	s_add_i32 s6, s39, s6
	s_ashr_i32 s6, s6, 6
	s_cmp_lt_u32 s6, 16
	s_brev_b32 s17, 16
	s_cselect_b32 s17, s17, 0xc002800
	s_mov_b32 s18, 0x8000800
	s_mov_b32 s19, 0xc001000
	s_cselect_b32 s18, s18, 0xc003000
	s_cselect_b32 s19, s19, 0xc003800
	s_cselect_b32 s23, 0x800, s59
	s_add_u32 s17, s92, s17
	s_addc_u32 s26, s93, 0
	s_add_u32 s18, s92, s18
	s_addc_u32 s28, s93, 0
	s_add_u32 s19, s92, s19
	s_addc_u32 s29, s93, 0
	s_lshl_b32 s35, s6, 7
	s_and_b32 s35, s35, 0x600
	s_add_u32 s46, s17, s35
	s_addc_u32 s47, s26, 0
	s_add_u32 s48, s18, s35
	s_addc_u32 s49, s28, 0
	v_mov_b32_e32 v42, v90
	s_add_u32 s50, s19, s35
	s_addc_u32 s51, s29, 0
	v_lshlrev_b32_e32 v0, 4, v42
	s_lshl_b32 s17, s6, 12
	v_and_b32_e32 v0, 0x1f0, v0
	s_and_b32 s17, s17, 0x3000
	v_lshl_add_u64 v[2:3], s[46:47], 0, v[0:1]
	v_lshl_add_u64 v[4:5], s[48:49], 0, v[0:1]
	v_lshl_add_u64 v[6:7], s[50:51], 0, v[0:1]
	v_ashrrev_i32_e32 v0, 5, v42
	v_add_u32_e32 v0, s17, v0
	s_lshl_b32 s6, s6, 12
	v_subrev_u32_e32 v0, s6, v0
	s_add_i32 s18, s31, s38
	v_add_u32_e32 v0, s18, v0
	v_mad_i64_i32 v[8:9], s[46:47], s23, v0, 0
	v_lshlrev_b64 v[8:9], 1, v[8:9]
	v_lshl_add_u64 v[10:11], v[2:3], 0, v[8:9]
	v_lshl_add_u64 v[8:9], v[4:5], 0, v[8:9]
	global_load_dwordx4 v[14:17], v[10:11], off
	s_nop 0
	global_load_dwordx4 v[10:13], v[8:9], off
	v_mad_i64_i32 v[8:9], s[46:47], v0, s96, v[6:7]
	v_add_u32_e32 v0, 0x200, v42
	v_ashrrev_i32_e32 v0, 5, v0
	v_add_u32_e32 v0, s17, v0
	v_subrev_u32_e32 v0, s6, v0
	v_add_u32_e32 v0, s18, v0
	v_mad_i64_i32 v[18:19], s[46:47], s23, v0, 0
	v_lshlrev_b64 v[18:19], 1, v[18:19]
	v_lshl_add_u64 v[20:21], v[2:3], 0, v[18:19]
	global_load_dwordx4 v[34:37], v[8:9], off
	global_load_dwordx4 v[38:41], v[20:21], off
	v_lshl_add_u64 v[8:9], v[4:5], 0, v[18:19]
	v_mad_i64_i32 v[18:19], s[46:47], v0, s96, v[6:7]
	v_add_u32_e32 v0, 0x400, v42
	v_ashrrev_i32_e32 v0, 5, v0
	v_add_u32_e32 v0, s17, v0
	v_subrev_u32_e32 v0, s6, v0
	v_add_u32_e32 v0, s18, v0
	global_load_dwordx4 v[22:25], v[8:9], off
	s_nop 0
	global_load_dwordx4 v[18:21], v[18:19], off
	v_mad_i64_i32 v[8:9], s[46:47], s23, v0, 0
	v_lshlrev_b64 v[8:9], 1, v[8:9]
	v_lshl_add_u64 v[26:27], v[2:3], 0, v[8:9]
	v_lshl_add_u64 v[8:9], v[4:5], 0, v[8:9]
	global_load_dwordx4 v[30:33], v[26:27], off
	s_nop 0
	global_load_dwordx4 v[26:29], v[8:9], off
	v_mad_i64_i32 v[8:9], s[46:47], v0, s96, v[6:7]
	v_add_u32_e32 v0, 0x600, v42
	v_ashrrev_i32_e32 v0, 5, v0
	v_add_u32_e32 v0, s17, v0
	v_subrev_u32_e32 v0, s6, v0
	v_add_u32_e32 v0, s18, v0
	v_mad_i64_i32 v[42:43], s[46:47], s23, v0, 0
	v_lshlrev_b64 v[50:51], 1, v[42:43]
	v_lshl_add_u64 v[2:3], v[2:3], 0, v[50:51]
	global_load_dwordx4 v[42:45], v[8:9], off
	global_load_dwordx4 v[46:49], v[2:3], off
	v_lshl_add_u64 v[2:3], v[4:5], 0, v[50:51]
	v_mad_i64_i32 v[4:5], s[46:47], v0, s96, v[6:7]
	global_load_dwordx4 v[6:9], v[2:3], off
	s_nop 0
	global_load_dwordx4 v[2:5], v[4:5], off

; #define LAS __attribute__((address_space(3)))
; DI void phase_ps(const Params& p, int seg, LAS unsigned char* lds, int G, int bid) {
;     ...
;           float pw[8];
; #pragma unroll
;           for (int r = 0; r < 4; ++r) { const int s0 = 32 * ks + 4 * g4 + r; pw[r] = (s0 <= lq) ? sa0[r] : 0.f; pw[4 + r] = (s0 + 16 <= lq) ? sa1[r] : 0.f; }
;           u32x2 w0, w1; w0.x = cvt_pk_bf16(pw[0], pw[1]); w0.y = cvt_pk_bf16(pw[2], pw[3]); w1.x = cvt_pk_bf16(pw[4], pw[5]); w1.y = cvt_pk_bf16(pw[6], pw[7]);
;           *(LAS u32x2*)(lds + PS_PI + lq * PS_PP + (32 * ks + 4 * g4) * 2) = w0;
;           *(LAS u32x2*)(lds + PS_PI + lq * PS_PP + (32 * ks + 16 + 4 * g4) * 2) = w1; }
;         MX_BAR();
;         { int ln = lane; asm volatile("" : "+v"(ln)); const int i16 = ln & 15, g4 = ln >> 4;
;           s16x4 t[8];
;           const unsigned va = ldsb + PS_VI + (8 * g4 + (i16 >> 2)) * QP + (2 * wave) * 32 + 8 * (ln & 3);
;           asm volatile("ds_read_b64_tr_b16 %0, %8\n\tds_read_b64_tr_b16 %1, %8 offset:2112\n\tds_read_b64_tr_b16 %2, %8 offset:16896\n\tds_read_b64_tr_b16 %3, %8 offset:19008\n\t"
;                        "ds_read_b64_tr_b16 %4, %8 offset:32\n\tds_read_b64_tr_b16 %5, %8 offset:2144\n\tds_read_b64_tr_b16 %6, %8 offset:16928\n\tds_read_b64_tr_b16 %7, %8 offset:19040\n\ts_waitcnt lgkmcnt(0)"
;                        : "=&v"(t[0]), "=&v"(t[1]), "=&v"(t[2]), "=&v"(t[3]), "=&v"(t[4]), "=&v"(t[5]), "=&v"(t[6]), "=&v"(t[7]) : "v"(va) : "memory");
;           bf16x8 pf[4][2];
; #pragma unroll
;           for (int lt = 0; lt < 4; ++lt)
; #pragma unroll
;               for (int kk = 0; kk < 2; ++kk) pf[lt][kk] = *(const LAS bf16x8*)(lds + PS_PI + (16 * lt + i16) * PS_PP + 64 * kk + 16 * g4);
;           __builtin_amdgcn_sched_barrier(0);
; #pragma unroll
;           for (int a = 0; a < 2; ++a) {
;               const bf16x8 v0 = __builtin_shufflevector(t[4 * a], t[4 * a + 1], 0, 1, 2, 3, 4, 5, 6, 7), v1 = __builtin_shufflevector(t[4 * a + 2], t[4 * a + 3], 0, 1, 2, 3, 4, 5, 6, 7);
; #pragma unroll
;               for (int lt = 0; lt < 4; ++lt) {
;                   f32x4 o = __builtin_amdgcn_mfma_f32_16x16x32_bf16(v0, pf[lt][0], (f32x4){0.f, 0.f, 0.f, 0.f}, 0, 0, 0);
;                   o = __builtin_amdgcn_mfma_f32_16x16x32_bf16(v1, pf[lt][1], o, 0, 0, 0);
;                   u32x2 w; w.x = cvt_pk_bf16(o[0], o[1]); w.y = cvt_pk_bf16(o[2], o[3]);
.LBB0_500:
	s_ashr_i32 s6, s22, 31
	v_ashrrev_i32_e32 v58, 2, v58
	s_lshr_b32 s6, s6, 26
	v_and_b32_e32 v58, -4, v58
	s_add_i32 s6, s22, s6
	v_add_u32_e32 v59, s9, v58
	s_ashr_i32 s35, s6, 6
	v_cvt_pk_bf16_f32 v54, v54, s0
	v_cmp_le_i32_e32 vcc, v59, v0
	s_lshl_b32 s17, s35, 12
	v_cvt_pk_bf16_f32 v55, v55, s0
	v_cndmask_b32_e32 v54, 0, v54, vcc
	v_cmp_lt_i32_e32 vcc, v59, v0
	s_and_b32 s23, s17, 0x3000
	v_or_b32_e32 v61, 2, v59
	v_cndmask_b32_e32 v55, 0, v55, vcc
	s_mov_b32 s17, 0x5040100
	v_or_b32_e32 v62, 3, v59
	v_perm_b32 v54, v55, v54, s17
	v_cvt_pk_bf16_f32 v55, v56, s0
	v_cmp_le_i32_e32 vcc, v61, v0
	v_add_u32_e32 v60, -16, v0
	v_cvt_pk_bf16_f32 v56, v57, s0
	v_cndmask_b32_e32 v55, 0, v55, vcc
	v_cmp_le_i32_e32 vcc, v62, v0
	v_cvt_pk_bf16_f32 v50, v50, s0
	v_cvt_pk_bf16_f32 v51, v51, s0
	v_cndmask_b32_e32 v56, 0, v56, vcc
	v_cmp_le_i32_e32 vcc, v59, v60
	v_perm_b32 v55, v56, v55, s17
	s_and_b32 s46, s6, 0xfffffc00
	v_cndmask_b32_e32 v50, 0, v50, vcc
	v_cmp_lt_i32_e32 vcc, v59, v60
	s_ashr_i32 s47, s46, 31
	s_bfe_u32 s22, s35, 0x20002
	v_cndmask_b32_e32 v51, 0, v51, vcc
	v_perm_b32 v50, v51, v50, s17
	v_cvt_pk_bf16_f32 v51, v52, s0
	v_cmp_le_i32_e32 vcc, v61, v60
	v_cvt_pk_bf16_f32 v52, v53, s0
	s_lshl_b64 s[46:47], s[46:47], 1
	v_cndmask_b32_e32 v51, 0, v51, vcc
	v_cmp_le_i32_e32 vcc, v62, v60
	s_add_u32 s6, s24, s46
	s_nop 0
	v_cndmask_b32_e32 v52, 0, v52, vcc
	v_perm_b32 v51, v52, v51, s17
	v_mov_b32_e32 v52, s36
	v_mad_u32_u24 v0, v0, s82, v52
	v_lshl_add_u32 v52, v59, 1, v0
	ds_write_b64 v52, v[54:55]
	v_add_u32_e32 v52, s11, v58
	v_lshl_add_u32 v0, v52, 1, v0
	ds_write_b64 v0, v[50:51]
	v_mov_b32_e32 v0, v91
	s_waitcnt lgkmcnt(0)
	s_barrier
	s_addc_u32 s17, s25, s47
	v_ashrrev_i32_e32 v101, 4, v0
	v_bfe_u32 v50, v0, 2, 2
	v_lshl_or_b32 v50, v101, 3, v50
	v_lshlrev_b32_e32 v51, 3, v0
	v_mul_lo_u32 v50, v50, s34
	v_and_b32_e32 v51, 24, v51
	v_and_b32_e32 v100, 15, v0
	v_add3_u32 v54, s30, v51, v50
	ds_read_b64_tr_b16 v[96:97], v54
	ds_read_b64_tr_b16 v[98:99], v54 offset:2112
	ds_read_b64_tr_b16 v[92:93], v54 offset:16896
	ds_read_b64_tr_b16 v[94:95], v54 offset:19008
	ds_read_b64_tr_b16 v[58:59], v54 offset:32
	ds_read_b64_tr_b16 v[60:61], v54 offset:2144
	ds_read_b64_tr_b16 v[50:51], v54 offset:16928
	ds_read_b64_tr_b16 v[52:53], v54 offset:19040
	s_waitcnt lgkmcnt(0)
	v_and_b32_e32 v54, -16, v0
	v_mul_u32_u24_e32 v55, 0x90, v100
	v_add3_u32 v54, s36, v54, v55
	ds_read_b128 v[86:89], v54
	ds_read_b128 v[82:85], v54 offset:64
	ds_read_b128 v[78:81], v54 offset:2304
	ds_read_b128 v[74:77], v54 offset:2368
	ds_read_b128 v[70:73], v54 offset:4608
	ds_read_b128 v[66:69], v54 offset:4672
	ds_read_b128 v[62:65], v54 offset:6912
	ds_read_b128 v[54:57], v54 offset:6976
	s_lshl_b32 s18, s22, 9
	s_add_u32 s46, s6, s18
	s_addc_u32 s47, s17, 0
	v_or_b32_e32 v100, s23, v100
	s_lshl_b32 s26, s35, 12
	v_subrev_u32_e32 v100, s26, v100
	v_add_u32_e32 v106, s38, v100
	v_lshlrev_b32_e32 v100, 2, v101
	v_ashrrev_i32_e32 v101, 31, v100
	v_lshl_add_u64 v[100:101], v[100:101], 1, s[46:47]
	v_lshl_add_u64 v[104:105], s[40:41], 1, v[100:101]
	s_waitcnt lgkmcnt(7)
	v_mfma_f32_16x16x32_bf16 v[100:103], v[96:99], v[86:89], 0
	s_mov_b32 s6, 0x48000
	s_cmp_lt_u32 s35, 16
	s_cselect_b64 s[46:47], -1, 0
	s_waitcnt lgkmcnt(6)
	v_mfma_f32_16x16x32_bf16 v[100:103], v[92:95], v[82:85], v[100:103]
	s_and_b64 s[46:47], s[46:47], s[42:43]
	v_mfma_f32_16x16x32_bf16 v[86:89], v[58:61], v[86:89], 0
	v_mfma_f32_16x16x32_bf16 v[82:85], v[50:53], v[82:85], v[86:89]
	s_nop 4
	v_cvt_pk_bf16_f32 v100, v100, v101
	v_cvt_pk_bf16_f32 v101, v102, v103
	v_mul_lo_u32 v102, v106, s59
	v_ashrrev_i32_e32 v103, 31, v102
	v_lshl_add_u64 v[104:105], v[102:103], 1, v[104:105]
	global_store_dwordx2 v[104:105], v[100:101], off
	s_waitcnt lgkmcnt(5)
	v_mfma_f32_16x16x32_bf16 v[100:103], v[96:99], v[78:81], 0
	v_add_co_u32_e32 v106, vcc, s6, v104
	s_mov_b32 s6, 0x90000
	s_waitcnt lgkmcnt(4)
	v_mfma_f32_16x16x32_bf16 v[100:103], v[92:95], v[74:77], v[100:103]
	v_addc_co_u32_e32 v107, vcc, 0, v105, vcc
	v_cvt_pk_bf16_f32 v82, v82, v83
	v_mfma_f32_16x16x32_bf16 v[78:81], v[58:61], v[78:81], 0
	v_cvt_pk_bf16_f32 v83, v84, v85
	s_nop 3
	v_cvt_pk_bf16_f32 v100, v100, v101
	v_cvt_pk_bf16_f32 v101, v102, v103
	global_store_dwordx2 v[106:107], v[100:101], off
	s_waitcnt lgkmcnt(3)
	v_mfma_f32_16x16x32_bf16 v[100:103], v[96:99], v[70:73], 0
	global_store_dwordx2 v[104:105], v[82:83], off offset:32
	s_waitcnt lgkmcnt(1)
	v_mfma_f32_16x16x32_bf16 v[96:99], v[96:99], v[62:65], 0
	v_mfma_f32_16x16x32_bf16 v[100:103], v[92:95], v[66:69], v[100:103]
	v_mfma_f32_16x16x32_bf16 v[70:73], v[58:61], v[70:73], 0
	v_mfma_f32_16x16x32_bf16 v[58:61], v[58:61], v[62:65], 0
	s_nop 5
	v_cvt_pk_bf16_f32 v100, v100, v101
	v_cvt_pk_bf16_f32 v101, v102, v103
	v_add_co_u32_e32 v102, vcc, s6, v104
	s_waitcnt lgkmcnt(0)
	v_mfma_f32_16x16x32_bf16 v[92:95], v[92:95], v[54:57], v[96:99]
	v_addc_co_u32_e32 v103, vcc, 0, v105, vcc
	s_mov_b32 s6, 0xd8000
	v_mfma_f32_16x16x32_bf16 v[74:77], v[50:53], v[74:77], v[78:81]
	global_store_dwordx2 v[102:103], v[100:101], off
	s_nop 3
	v_cvt_pk_bf16_f32 v92, v92, v93
	v_cvt_pk_bf16_f32 v93, v94, v95
	v_mfma_f32_16x16x32_bf16 v[66:69], v[50:53], v[66:69], v[70:73]
	v_add_co_u32_e32 v94, vcc, s6, v104
	v_cvt_pk_bf16_f32 v74, v74, v75
	v_mfma_f32_16x16x32_bf16 v[50:53], v[50:53], v[54:57], v[58:61]
	v_addc_co_u32_e32 v95, vcc, 0, v105, vcc
	v_cvt_pk_bf16_f32 v75, v76, v77
	s_nop 2
	v_cvt_pk_bf16_f32 v66, v66, v67
	v_cvt_pk_bf16_f32 v67, v68, v69
	s_nop 0
	v_cvt_pk_bf16_f32 v50, v50, v51
	v_cvt_pk_bf16_f32 v51, v52, v53
	s_andn2_b64 vcc, exec, s[46:47]
	global_store_dwordx2 v[94:95], v[92:93], off
	global_store_dwordx2 v[106:107], v[74:75], off offset:32
	global_store_dwordx2 v[102:103], v[66:67], off offset:32
	global_store_dwordx2 v[94:95], v[50:51], off offset:32
	s_cbranch_vccnz .LBB0_495
; #define LAS __attribute__((address_space(3)))
; #define MX_BAR() do { asm volatile("s_waitcnt lgkmcnt(0)" ::: "memory"); __builtin_amdgcn_s_barrier(); asm volatile("" ::: "memory"); } while (0)
; DI void phase_ps(const Params& p, int seg, LAS unsigned char* lds, int G, int bid) {
;     ...
;           if (grp == 0 && wave == 0) { float sum = 0.f;
; #pragma unroll
;               for (int c = 0; c < 8; ++c) { const u32x4 pr = *(const LAS u32x4*)(lds + PS_PI + ln * PS_PP + 16 * c);
; #pragma unroll
;                   for (int q = 0; q < 4; ++q) sum += bflo(pr[q]) + bfhi(pr[q]); }
;               dnb[(size_t)(lrow0 + ln) * 4 + hh] = sum; }
;         }
;         MX_BAR();
	v_mul_lo_u32 v50, v0, s82
	v_add_u32_e32 v50, 0, v50
	v_add_u32_e32 v66, 0x18c00, v50
	ds_read_b128 v[50:53], v66
	ds_read_b128 v[54:57], v66 offset:16
	ds_read_b128 v[58:61], v66 offset:32
	ds_read_b128 v[62:65], v66 offset:48
	v_add_u32_e32 v0, s23, v0
	s_waitcnt lgkmcnt(3)
	v_lshlrev_b32_e32 v67, 16, v50
	v_and_b32_e32 v50, 0xffff0000, v50
	v_add_f32_e32 v50, v67, v50
	v_lshlrev_b32_e32 v67, 16, v51
	v_and_b32_e32 v51, 0xffff0000, v51
	v_add_f32_e32 v50, 0, v50
	v_add_f32_e32 v51, v67, v51
	v_add_f32_e32 v50, v51, v50
	v_lshlrev_b32_e32 v51, 16, v52
	v_and_b32_e32 v52, 0xffff0000, v52
	v_add_f32_e32 v51, v51, v52
	v_add_f32_e32 v50, v51, v50
	v_lshlrev_b32_e32 v51, 16, v53
	v_and_b32_e32 v52, 0xffff0000, v53
	v_add_f32_e32 v51, v51, v52
	v_add_f32_e32 v50, v51, v50
	s_waitcnt lgkmcnt(2)
	v_lshlrev_b32_e32 v51, 16, v54
	v_and_b32_e32 v52, 0xffff0000, v54
	v_add_f32_e32 v51, v51, v52
	v_add_f32_e32 v50, v51, v50
	v_lshlrev_b32_e32 v51, 16, v55
	v_and_b32_e32 v52, 0xffff0000, v55
	v_add_f32_e32 v51, v51, v52
	v_add_f32_e32 v50, v51, v50
	v_lshlrev_b32_e32 v51, 16, v56
	v_and_b32_e32 v52, 0xffff0000, v56
	v_add_f32_e32 v51, v51, v52
	v_add_f32_e32 v50, v51, v50
	v_lshlrev_b32_e32 v51, 16, v57
	v_and_b32_e32 v52, 0xffff0000, v57
	v_add_f32_e32 v51, v51, v52
	v_add_f32_e32 v50, v51, v50
	s_waitcnt lgkmcnt(1)
	v_lshlrev_b32_e32 v51, 16, v58
	v_and_b32_e32 v52, 0xffff0000, v58
	v_add_f32_e32 v51, v51, v52
	v_add_f32_e32 v50, v51, v50
	v_lshlrev_b32_e32 v51, 16, v59
	v_and_b32_e32 v52, 0xffff0000, v59
	v_add_f32_e32 v51, v51, v52
	v_add_f32_e32 v50, v51, v50
	v_lshlrev_b32_e32 v51, 16, v60
	v_and_b32_e32 v52, 0xffff0000, v60
	v_add_f32_e32 v51, v51, v52
	v_add_f32_e32 v50, v51, v50
	v_lshlrev_b32_e32 v51, 16, v61
	v_and_b32_e32 v52, 0xffff0000, v61
	v_add_f32_e32 v51, v51, v52
	v_add_f32_e32 v50, v51, v50
	s_waitcnt lgkmcnt(0)
	v_lshlrev_b32_e32 v51, 16, v62
	v_and_b32_e32 v52, 0xffff0000, v62
	v_add_f32_e32 v51, v51, v52
	v_add_f32_e32 v50, v51, v50
	v_lshlrev_b32_e32 v51, 16, v63
	v_and_b32_e32 v52, 0xffff0000, v63
	v_add_f32_e32 v51, v51, v52
	v_add_f32_e32 v50, v51, v50
	v_lshlrev_b32_e32 v51, 16, v64
	v_and_b32_e32 v52, 0xffff0000, v64
	v_add_f32_e32 v51, v51, v52
	v_add_f32_e32 v54, v51, v50
	ds_read_b128 v[50:53], v66 offset:64
	v_lshlrev_b32_e32 v55, 16, v65
	v_and_b32_e32 v56, 0xffff0000, v65
	v_add_f32_e32 v55, v55, v56
	v_add_f32_e32 v58, v55, v54
	ds_read_b128 v[54:57], v66 offset:80
	s_waitcnt lgkmcnt(1)
	v_lshlrev_b32_e32 v59, 16, v50
	v_and_b32_e32 v50, 0xffff0000, v50
	v_add_f32_e32 v50, v59, v50
	v_add_f32_e32 v50, v50, v58
	v_lshlrev_b32_e32 v58, 16, v51
	v_and_b32_e32 v51, 0xffff0000, v51
	v_add_f32_e32 v51, v58, v51
	v_add_f32_e32 v50, v51, v50
	v_lshlrev_b32_e32 v51, 16, v52
	v_and_b32_e32 v52, 0xffff0000, v52
	v_add_f32_e32 v51, v51, v52
	v_add_f32_e32 v50, v51, v50
	v_lshlrev_b32_e32 v51, 16, v53
	v_and_b32_e32 v52, 0xffff0000, v53
	v_add_f32_e32 v51, v51, v52
	v_add_f32_e32 v58, v51, v50
	s_waitcnt lgkmcnt(0)
	v_lshlrev_b32_e32 v51, 16, v55
	v_lshlrev_b32_e32 v50, 16, v54
	v_and_b32_e32 v53, 0xffff0000, v55
	v_and_b32_e32 v52, 0xffff0000, v54
	v_pk_add_f32 v[50:51], v[50:51], v[52:53]
	v_lshlrev_b32_e32 v55, 16, v57
	v_add_f32_e32 v50, v50, v58
	v_add_f32_e32 v58, v51, v50
	ds_read_b128 v[50:53], v66 offset:96
	v_lshlrev_b32_e32 v54, 16, v56
	v_and_b32_e32 v57, 0xffff0000, v57
	v_and_b32_e32 v56, 0xffff0000, v56
	v_pk_add_f32 v[54:55], v[54:55], v[56:57]
	v_subrev_u32_e32 v0, s26, v0
	v_add_f32_e32 v54, v54, v58
	v_add_f32_e32 v60, v55, v54
	ds_read_b128 v[54:57], v66 offset:112
	s_waitcnt lgkmcnt(1)
	v_lshlrev_b32_e32 v59, 16, v51
	v_lshlrev_b32_e32 v58, 16, v50
	v_and_b32_e32 v51, 0xffff0000, v51
	v_and_b32_e32 v50, 0xffff0000, v50
	v_pk_add_f32 v[50:51], v[58:59], v[50:51]
	v_readlane_b32 s18, v251, 29
	v_add_f32_e32 v50, v50, v60
	v_add_f32_e32 v58, v51, v50
	v_lshlrev_b32_e32 v51, 16, v53
	v_lshlrev_b32_e32 v50, 16, v52
	v_and_b32_e32 v53, 0xffff0000, v53
	v_and_b32_e32 v52, 0xffff0000, v52
	v_pk_add_f32 v[50:51], v[50:51], v[52:53]
	s_waitcnt lgkmcnt(0)
	v_and_b32_e32 v53, 0xffff0000, v55
	v_add_f32_e32 v50, v50, v58
	v_add_f32_e32 v58, v51, v50
	v_lshlrev_b32_e32 v51, 16, v55
	v_lshlrev_b32_e32 v50, 16, v54
	v_and_b32_e32 v52, 0xffff0000, v54
	v_pk_add_f32 v[50:51], v[50:51], v[52:53]
	v_and_b32_e32 v53, 0xffff0000, v57
	v_add_f32_e32 v50, v50, v58
	v_add_f32_e32 v54, v51, v50
	v_lshlrev_b32_e32 v51, 16, v57
	v_lshlrev_b32_e32 v50, 16, v56
	v_and_b32_e32 v52, 0xffff0000, v56
	v_pk_add_f32 v[50:51], v[50:51], v[52:53]
	v_readlane_b32 s19, v251, 30
	v_add_f32_e32 v50, v50, v54
	v_add_f32_e32 v52, v51, v50
	v_add_u32_e32 v50, s38, v0
	v_ashrrev_i32_e32 v51, 31, v50
	v_lshl_add_u64 v[50:51], v[50:51], 4, s[18:19]
	s_lshl_b32 s26, s22, 2
	v_lshl_add_u64 v[50:51], v[50:51], 0, s[26:27]
	global_store_dword v[50:51], v52, off
	s_branch .LBB0_495
